# 64-step chain: output-section loads no longer queue behind the cross-chunk prefetch group (gain loads issued ahead of it, next chunk's gate rows fetched at the end of the output section, counted waits
# baseline (speedup 1.0000x reference)
.LBB0_1053:
	s_waitcnt vmcnt(0)
	s_ashr_i32 s29, s28, 31
	s_lshl_b64 s[0:1], s[28:29], 16
	s_add_u32 s0, s5, s0
	s_addc_u32 s1, s12, s1
	v_lshl_add_u64 v[32:33], v[64:65], 2, s[0:1]
	v_lshlrev_b32_e32 v124, 11, v71
	v_lshlrev_b32_e32 v38, 9, v108
	v_lshl_add_u64 v[34:35], v[32:33], 0, v[124:125]
	v_lshlrev_b32_e32 v124, 9, v111
	v_lshl_add_u64 v[36:37], v[32:33], 0, v[124:125]
	v_or_b32_e32 v124, 0x400, v38
	global_store_dword v[34:35], v28, off
	global_store_dword v[36:37], v29, off
	v_lshl_add_u64 v[28:29], v[32:33], 0, v[124:125]
	v_or_b32_e32 v124, 0x600, v38
	global_store_dword v[28:29], v30, off
	v_lshl_add_u64 v[28:29], v[32:33], 0, v[124:125]
	v_or_b32_e32 v124, 0x2000, v38
	global_store_dword v[28:29], v31, off
	v_lshl_add_u64 v[28:29], v[32:33], 0, v[124:125]
	v_or_b32_e32 v124, 0x2200, v38
	global_store_dword v[28:29], v20, off
	v_lshl_add_u64 v[28:29], v[32:33], 0, v[124:125]
	v_or_b32_e32 v124, 0x2400, v38
	global_store_dword v[28:29], v21, off
	v_lshl_add_u64 v[20:21], v[32:33], 0, v[124:125]
	v_or_b32_e32 v124, 0x2600, v38
	global_store_dword v[20:21], v22, off
	v_lshl_add_u64 v[20:21], v[32:33], 0, v[124:125]
	v_or_b32_e32 v124, 0x4000, v38
	global_store_dword v[20:21], v23, off
	v_lshl_add_u64 v[20:21], v[32:33], 0, v[124:125]
	v_or_b32_e32 v124, 0x4200, v38
	global_store_dword v[20:21], v0, off
	v_lshl_add_u64 v[20:21], v[32:33], 0, v[124:125]
	v_or_b32_e32 v124, 0x4400, v38
	global_store_dword v[20:21], v1, off
	v_lshl_add_u64 v[0:1], v[32:33], 0, v[124:125]
	v_or_b32_e32 v124, 0x4600, v38
	global_store_dword v[0:1], v2, off
	v_lshl_add_u64 v[0:1], v[32:33], 0, v[124:125]
	v_or_b32_e32 v124, 0x6000, v38
	global_store_dword v[0:1], v3, off
	v_lshl_add_u64 v[0:1], v[32:33], 0, v[124:125]
	v_or_b32_e32 v124, 0x6200, v38
	global_store_dword v[0:1], v16, off
	v_lshl_add_u64 v[0:1], v[32:33], 0, v[124:125]
	v_or_b32_e32 v124, 0x6400, v38
	global_store_dword v[0:1], v17, off
	v_lshl_add_u64 v[0:1], v[32:33], 0, v[124:125]
	v_or_b32_e32 v124, 0x6600, v38
	global_store_dword v[0:1], v18, off
	v_lshl_add_u64 v[0:1], v[32:33], 0, v[124:125]
	s_mov_b32 s0, 0x8000
	global_store_dword v[0:1], v19, off
	v_add_co_u32_e32 v0, vcc, s0, v34
	s_mov_b32 s0, 0xa000
	s_nop 0
	v_addc_co_u32_e32 v1, vcc, 0, v35, vcc
	global_store_dword v[0:1], v4, off
	global_store_dword v[0:1], v5, off offset:512
	global_store_dword v[0:1], v6, off offset:1024
	global_store_dword v[0:1], v7, off offset:1536
	v_add_co_u32_e32 v0, vcc, s0, v34
	s_nop 1
	v_addc_co_u32_e32 v1, vcc, 0, v35, vcc
	global_store_dword v[0:1], v12, off
	global_store_dword v[0:1], v13, off offset:512
	global_store_dword v[0:1], v14, off offset:1024
	global_store_dword v[0:1], v15, off offset:1536
	v_add_co_u32_e32 v0, vcc, 0xc000, v34
	s_nop 1
	v_addc_co_u32_e32 v1, vcc, 0, v35, vcc
	global_store_dword v[0:1], v8, off
	global_store_dword v[0:1], v9, off offset:512
	global_store_dword v[0:1], v10, off offset:1024
	global_store_dword v[0:1], v11, off offset:1536
	v_add_co_u32_e32 v0, vcc, 0xe000, v34
	s_nop 1
	v_addc_co_u32_e32 v1, vcc, 0, v35, vcc
	global_store_dword v[0:1], v24, off
	global_store_dword v[0:1], v25, off offset:512
	global_store_dword v[0:1], v26, off offset:1024
	global_store_dword v[0:1], v27, off offset:1536

.LBB0_1098:
	s_lshl_b32 s10, s0, 4
	s_add_i32 s10, s1, s10
	s_ashr_i32 s11, s10, 31
	s_mul_i32 s29, s10, 0x12000
	s_mul_hi_i32 s26, s10, 0x12000
	s_add_u32 s30, s19, s29
	s_addc_u32 s31, s42, s26
	s_lshl_b64 s[10:11], s[10:11], 2
	s_add_u32 s10, s43, s10
	s_addc_u32 s11, s4, s11
	s_cmp_lg_u32 s0, 0
	s_cbranch_scc1 .Lck64_ldskip
	global_load_dword v228, v125, s[10:11] sc1
	v_add_u32_e32 v40, 0x2000, v113
	v_add_u32_e32 v41, 0x8000, v113
	v_add_u32_e32 v38, 0xa000, v113
	v_add_u32_e32 v39, 0xc000, v113
	v_add_u32_e32 v34, 0xe000, v113
	v_add_u32_e32 v35, 0x10000, v113
	global_load_dwordx4 v[166:169], v113, s[30:31]
	global_load_dwordx4 v[170:173], v40, s[30:31]
	global_load_dwordx4 v[174:177], v41, s[30:31]
	global_load_dwordx4 v[178:181], v38, s[30:31]
	global_load_dwordx4 v[182:185], v39, s[30:31]
	global_load_dwordx4 v[186:189], v34, s[30:31]
	global_load_dwordx4 v[190:193], v35, s[30:31]
	v_lshl_add_u64 v[226:227], s[30:31], 0, v[72:73]
	v_lshl_add_u64 v[226:227], v[226:227], 0, v[68:69]
	s_mov_b64 s[10:11], 0x4000
	v_lshl_add_u64 v[226:227], v[226:227], 0, s[10:11]
	global_load_dwordx2 v[214:215], v[226:227], off
	global_load_dwordx2 v[216:217], v[226:227], off offset:32
	global_load_dwordx2 v[218:219], v[226:227], off offset:64
	global_load_dwordx2 v[220:221], v[226:227], off offset:96
	v_lshl_add_u32 v226, s0, 6, v112
	v_ashrrev_i32_e32 v227, 31, v226
	v_lshlrev_b64 v[226:227], 12, v[226:227]
	v_lshl_or_b32 v226, v70, 1, v226
	v_lshl_add_u64 v[226:227], s[46:47], 0, v[226:227]
	global_load_dwordx4 v[232:235], v[226:227], off
	global_load_dwordx4 v[236:239], v[226:227], off offset:16
	s_waitcnt vmcnt(0)
.Lck64_ldskip:
	v_ashrrev_i32_e32 v32, 4, v67
	v_mul_u32_u24_e32 v32, 0x110, v32
	v_and_b32_e32 v33, 15, v67
	v_lshl_add_u32 v32, v33, 4, v32
	v_ashrrev_i32_e32 v33, 3, v67
	v_lshl_add_u32 v33, v33, 4, v113
	s_waitcnt lgkmcnt(0)
	s_barrier
	s_waitcnt vmcnt(14)
	v_mov_b32_e32 v56, v228
	ds_write_b128 v32, v[166:169] offset:0
	s_waitcnt vmcnt(13)
	ds_write_b128 v32, v[170:173] offset:8704
	s_waitcnt vmcnt(12)
	ds_write_b128 v32, v[174:177] offset:17408
	s_waitcnt vmcnt(11)
	ds_write_b128 v32, v[178:181] offset:26112
	s_waitcnt vmcnt(10)
	ds_write_b128 v33, v[182:185] offset:34816
	s_waitcnt vmcnt(9)
	ds_write_b128 v33, v[186:189] offset:44032
	s_waitcnt vmcnt(8)
	ds_write_b128 v33, v[190:193] offset:53248
	v_add_u32_e32 v57, v110, v68
	v_add_u32_e32 v36, v66, v109
	s_waitcnt lgkmcnt(0)
	s_barrier
	ds_read_b128 v[52:55], v36 offset:62464
	ds_read_b128 v[48:51], v36 offset:62528
	ds_read_b128 v[44:47], v36 offset:62592
	ds_read_b128 v[40:43], v36 offset:62656
	ds_read_b128 v[138:141], v114 offset:0
	ds_read_b128 v[142:145], v114 offset:64
	ds_read_b128 v[146:149], v114 offset:128
	ds_read_b128 v[150:153], v114 offset:192
	ds_read_b128 v[194:197], v114 offset:4352
	ds_read_b128 v[198:201], v114 offset:4416
	ds_read_b128 v[202:205], v114 offset:4480
	ds_read_b128 v[206:209], v114 offset:4544
	s_waitcnt lgkmcnt(7)
	v_mfma_f32_16x16x32_bf16 v[154:157], v[138:141], v[52:55], 0
	s_waitcnt lgkmcnt(6)
	v_mfma_f32_16x16x32_bf16 v[154:157], v[142:145], v[48:51], v[154:157]
	s_waitcnt lgkmcnt(5)
	v_mfma_f32_16x16x32_bf16 v[154:157], v[146:149], v[44:47], v[154:157]
	s_waitcnt lgkmcnt(4)
	v_mfma_f32_16x16x32_bf16 v[154:157], v[150:153], v[40:43], v[154:157]
	ds_read_b128 v[138:141], v114 offset:8704
	ds_read_b128 v[142:145], v114 offset:8768
	ds_read_b128 v[146:149], v114 offset:8832
	ds_read_b128 v[150:153], v114 offset:8896
	s_waitcnt lgkmcnt(7)
	v_mfma_f32_16x16x32_bf16 v[210:213], v[194:197], v[52:55], 0
	s_waitcnt lgkmcnt(6)
	v_mfma_f32_16x16x32_bf16 v[210:213], v[198:201], v[48:51], v[210:213]
	s_waitcnt lgkmcnt(5)
	v_mfma_f32_16x16x32_bf16 v[210:213], v[202:205], v[44:47], v[210:213]
	s_waitcnt lgkmcnt(4)
	v_mfma_f32_16x16x32_bf16 v[210:213], v[206:209], v[40:43], v[210:213]
	s_waitcnt vmcnt(7)
	v_lshlrev_b32_e32 v222, 16, v214
	v_and_b32_e32 v223, 0xffff0000, v214
	v_lshlrev_b32_e32 v224, 16, v215
	v_and_b32_e32 v225, 0xffff0000, v215
	v_pk_add_f32 v[154:155], v[222:223], v[154:155] neg_lo:[0,1] neg_hi:[0,1]
	v_pk_add_f32 v[156:157], v[224:225], v[156:157] neg_lo:[0,1] neg_hi:[0,1]
	v_cvt_pk_bf16_f32 v154, v154, v155
	v_cvt_pk_bf16_f32 v155, v156, v157
	ds_write_b64 v57, v[154:155]
	ds_read_b128 v[194:197], v114 offset:13056
	ds_read_b128 v[198:201], v114 offset:13120
	ds_read_b128 v[202:205], v114 offset:13184
	ds_read_b128 v[206:209], v114 offset:13248
	s_waitcnt lgkmcnt(8)
	v_mfma_f32_16x16x32_bf16 v[154:157], v[138:141], v[52:55], 0
	s_waitcnt lgkmcnt(7)
	v_mfma_f32_16x16x32_bf16 v[154:157], v[142:145], v[48:51], v[154:157]
	s_waitcnt lgkmcnt(6)
	v_mfma_f32_16x16x32_bf16 v[154:157], v[146:149], v[44:47], v[154:157]
	s_waitcnt lgkmcnt(5)
	v_mfma_f32_16x16x32_bf16 v[154:157], v[150:153], v[40:43], v[154:157]
	s_waitcnt vmcnt(6)
	v_lshlrev_b32_e32 v222, 16, v216
	v_and_b32_e32 v223, 0xffff0000, v216
	v_lshlrev_b32_e32 v224, 16, v217
	v_and_b32_e32 v225, 0xffff0000, v217
	v_pk_add_f32 v[210:211], v[222:223], v[210:211] neg_lo:[0,1] neg_hi:[0,1]
	v_pk_add_f32 v[212:213], v[224:225], v[212:213] neg_lo:[0,1] neg_hi:[0,1]
	v_cvt_pk_bf16_f32 v210, v210, v211
	v_cvt_pk_bf16_f32 v211, v212, v213
	ds_write_b64 v57, v[210:211] offset:32
	s_waitcnt lgkmcnt(4)
	v_mfma_f32_16x16x32_bf16 v[210:213], v[194:197], v[52:55], 0
	s_waitcnt lgkmcnt(3)
	v_mfma_f32_16x16x32_bf16 v[210:213], v[198:201], v[48:51], v[210:213]
	s_waitcnt lgkmcnt(2)
	v_mfma_f32_16x16x32_bf16 v[210:213], v[202:205], v[44:47], v[210:213]
	s_waitcnt lgkmcnt(1)
	v_mfma_f32_16x16x32_bf16 v[210:213], v[206:209], v[40:43], v[210:213]
	s_waitcnt vmcnt(5)
	v_lshlrev_b32_e32 v222, 16, v218
	v_and_b32_e32 v223, 0xffff0000, v218
	v_lshlrev_b32_e32 v224, 16, v219
	v_and_b32_e32 v225, 0xffff0000, v219
	v_pk_add_f32 v[154:155], v[222:223], v[154:155] neg_lo:[0,1] neg_hi:[0,1]
	v_pk_add_f32 v[156:157], v[224:225], v[156:157] neg_lo:[0,1] neg_hi:[0,1]
	v_cvt_pk_bf16_f32 v154, v154, v155
	v_cvt_pk_bf16_f32 v155, v156, v157
	ds_write_b64 v57, v[154:155] offset:64
	s_nop 1
	s_waitcnt vmcnt(4)
	v_lshlrev_b32_e32 v222, 16, v220
	v_and_b32_e32 v223, 0xffff0000, v220
	v_lshlrev_b32_e32 v224, 16, v221
	v_and_b32_e32 v225, 0xffff0000, v221
	v_pk_add_f32 v[210:211], v[222:223], v[210:211] neg_lo:[0,1] neg_hi:[0,1]
	v_pk_add_f32 v[212:213], v[224:225], v[212:213] neg_lo:[0,1] neg_hi:[0,1]
	v_cvt_pk_bf16_f32 v210, v210, v211
	v_cvt_pk_bf16_f32 v211, v212, v213
	ds_write_b64 v57, v[210:211] offset:96
	v_add_u32_e32 v226, v110, v109
	s_waitcnt lgkmcnt(0)
	s_barrier
	ds_read_b128 v[36:39], v226
	ds_read_b128 v[32:35], v226 offset:64
	ds_read_b128 v[138:141], v114 offset:17408
	ds_read_b128 v[142:145], v114 offset:17472
	ds_read_b128 v[146:149], v114 offset:17536
	ds_read_b128 v[150:153], v114 offset:17600
	ds_read_b128 v[154:157], v115 offset:34816
	ds_read_b128 v[194:197], v115 offset:34880
	ds_read_b128 v[198:201], v114 offset:21760
	ds_read_b128 v[202:205], v114 offset:21824
	ds_read_b128 v[206:209], v114 offset:21888
	ds_read_b128 v[210:213], v114 offset:21952
	ds_read_b128 v[214:217], v115 offset:37120
	ds_read_b128 v[218:221], v115 offset:37184
	s_waitcnt lgkmcnt(11)
	v_mfma_f32_16x16x32_bf16 v[222:225], v[138:141], v[52:55], 0
	s_waitcnt lgkmcnt(10)
	v_mfma_f32_16x16x32_bf16 v[222:225], v[142:145], v[48:51], v[222:225]
	s_waitcnt lgkmcnt(9)
	v_mfma_f32_16x16x32_bf16 v[222:225], v[146:149], v[44:47], v[222:225]
	s_waitcnt lgkmcnt(8)
	v_mfma_f32_16x16x32_bf16 v[222:225], v[150:153], v[40:43], v[222:225]
	s_waitcnt lgkmcnt(7)
	v_mfma_f32_16x16x32_bf16 v[222:225], v[154:157], v[36:39], v[222:225]
	s_waitcnt lgkmcnt(6)
	v_mfma_f32_16x16x32_bf16 v[222:225], v[194:197], v[32:35], v[222:225]
	ds_read_b128 v[138:141], v114 offset:26112
	ds_read_b128 v[142:145], v114 offset:26176
	ds_read_b128 v[146:149], v114 offset:26240
	ds_read_b128 v[150:153], v114 offset:26304
	ds_read_b128 v[154:157], v115 offset:39424
	ds_read_b128 v[194:197], v115 offset:39488
	s_waitcnt lgkmcnt(11)
	v_mfma_f32_16x16x32_bf16 v[244:247], v[198:201], v[52:55], 0
	s_waitcnt lgkmcnt(10)
	v_mfma_f32_16x16x32_bf16 v[244:247], v[202:205], v[48:51], v[244:247]
	s_waitcnt lgkmcnt(9)
	v_mfma_f32_16x16x32_bf16 v[244:247], v[206:209], v[44:47], v[244:247]
	s_waitcnt lgkmcnt(8)
	v_mfma_f32_16x16x32_bf16 v[244:247], v[210:213], v[40:43], v[244:247]
	s_waitcnt lgkmcnt(7)
	v_mfma_f32_16x16x32_bf16 v[244:247], v[214:217], v[36:39], v[244:247]
	s_waitcnt lgkmcnt(6)
	v_mfma_f32_16x16x32_bf16 v[244:247], v[218:221], v[32:35], v[244:247]
	ds_read_b128 v[198:201], v114 offset:30464
	ds_read_b128 v[202:205], v114 offset:30528
	ds_read_b128 v[206:209], v114 offset:30592
	ds_read_b128 v[210:213], v114 offset:30656
	ds_read_b128 v[214:217], v115 offset:41728
	ds_read_b128 v[218:221], v115 offset:41792
	s_waitcnt lgkmcnt(11)
	v_mfma_f32_16x16x32_bf16 v[248:251], v[138:141], v[52:55], 0
	s_waitcnt lgkmcnt(10)
	v_mfma_f32_16x16x32_bf16 v[248:251], v[142:145], v[48:51], v[248:251]
	s_waitcnt lgkmcnt(9)
	v_mfma_f32_16x16x32_bf16 v[248:251], v[146:149], v[44:47], v[248:251]
	s_waitcnt lgkmcnt(8)
	v_mfma_f32_16x16x32_bf16 v[248:251], v[150:153], v[40:43], v[248:251]
	s_waitcnt lgkmcnt(7)
	v_mfma_f32_16x16x32_bf16 v[248:251], v[154:157], v[36:39], v[248:251]
	s_waitcnt lgkmcnt(6)
	v_mfma_f32_16x16x32_bf16 v[248:251], v[194:197], v[32:35], v[248:251]
	v_cvt_pk_bf16_f32 v57, v222, s0
	ds_write_b16 v116, v57
	v_cvt_pk_bf16_f32 v57, v223, s0
	ds_write_b16 v117, v57
	v_cvt_pk_bf16_f32 v57, v224, s0
	ds_write_b16 v117, v57 offset:272
	v_cvt_pk_bf16_f32 v57, v225, s0
	ds_write_b16 v117, v57 offset:544
	v_cvt_pk_bf16_f32 v57, v244, s0
	ds_write_b16 v117, v57 offset:4080
	v_cvt_pk_bf16_f32 v57, v245, s0
	ds_write_b16 v117, v57 offset:4352
	v_cvt_pk_bf16_f32 v57, v246, s0
	ds_write_b16 v117, v57 offset:4624
	v_cvt_pk_bf16_f32 v57, v247, s0
	ds_write_b16 v117, v57 offset:4896
	v_pk_mul_f32 v[30:31], v[30:31], v[56:57] op_sel_hi:[1,0]
	v_pk_mul_f32 v[28:29], v[28:29], v[56:57] op_sel_hi:[1,0]
	v_pk_mul_f32 v[22:23], v[22:23], v[56:57] op_sel_hi:[1,0]
	v_pk_mul_f32 v[20:21], v[20:21], v[56:57] op_sel_hi:[1,0]
	v_pk_mul_f32 v[2:3], v[2:3], v[56:57] op_sel_hi:[1,0]
	v_pk_mul_f32 v[0:1], v[0:1], v[56:57] op_sel_hi:[1,0]
	v_pk_mul_f32 v[18:19], v[18:19], v[56:57] op_sel_hi:[1,0]
	v_pk_mul_f32 v[16:17], v[16:17], v[56:57] op_sel_hi:[1,0]
	v_pk_mul_f32 v[6:7], v[6:7], v[56:57] op_sel_hi:[1,0]
	v_pk_mul_f32 v[4:5], v[4:5], v[56:57] op_sel_hi:[1,0]
	v_mul_f32_e64 v14, v14, v56
	v_mul_f32_e64 v15, v15, v56
	v_pk_mul_f32 v[12:13], v[12:13], v[56:57] op_sel_hi:[1,0]
	v_pk_mul_f32 v[10:11], v[10:11], v[56:57] op_sel_hi:[1,0]
	v_pk_mul_f32 v[8:9], v[8:9], v[56:57] op_sel_hi:[1,0]
	v_pk_mul_f32 v[26:27], v[26:27], v[56:57] op_sel_hi:[1,0]
	v_pk_mul_f32 v[24:25], v[24:25], v[56:57] op_sel_hi:[1,0]
	s_waitcnt lgkmcnt(13)
	v_mfma_f32_16x16x32_bf16 v[222:225], v[198:201], v[52:55], 0
	s_waitcnt lgkmcnt(12)
	v_mfma_f32_16x16x32_bf16 v[222:225], v[202:205], v[48:51], v[222:225]
	s_waitcnt lgkmcnt(11)
	v_mfma_f32_16x16x32_bf16 v[222:225], v[206:209], v[44:47], v[222:225]
	s_waitcnt lgkmcnt(10)
	v_mfma_f32_16x16x32_bf16 v[222:225], v[210:213], v[40:43], v[222:225]
	s_waitcnt lgkmcnt(9)
	v_mfma_f32_16x16x32_bf16 v[222:225], v[214:217], v[36:39], v[222:225]
	s_waitcnt lgkmcnt(8)
	v_mfma_f32_16x16x32_bf16 v[222:225], v[218:221], v[32:35], v[222:225]
	v_cvt_pk_bf16_f32 v57, v248, s0
	ds_write_b16 v117, v57 offset:8432
	v_cvt_pk_bf16_f32 v57, v249, s0
	ds_write_b16 v117, v57 offset:8704
	v_cvt_pk_bf16_f32 v57, v250, s0
	ds_write_b16 v117, v57 offset:8976
	v_cvt_pk_bf16_f32 v57, v251, s0
	ds_write_b16 v117, v57 offset:9248
	global_load_dwordx4 v[240:243], v[74:75], off offset:48
	global_load_dwordx4 v[40:43], v[74:75], off offset:32
	global_load_dwordx4 v[44:47], v[74:75], off offset:16
	global_load_dwordx4 v[48:51], v[74:75], off
	s_add_i32 s98, s0, 1
	s_lshl_b32 s98, s98, 4
	s_add_i32 s98, s1, s98
	s_ashr_i32 s99, s98, 31
	s_mul_i32 s100, s98, 0x12000
	s_mul_hi_i32 s101, s98, 0x12000
	s_add_u32 s100, s19, s100
	s_addc_u32 s101, s42, s101
	s_lshl_b64 s[98:99], s[98:99], 2
	s_add_u32 s98, s43, s98
	s_addc_u32 s99, s4, s99
	global_load_dword v228, v125, s[98:99] sc1
	v_add_u32_e32 v206, 0x2000, v113
	v_add_u32_e32 v207, 0x8000, v113
	v_add_u32_e32 v208, 0xa000, v113
	v_add_u32_e32 v209, 0xc000, v113
	v_add_u32_e32 v210, 0xe000, v113
	v_add_u32_e32 v211, 0x10000, v113
	global_load_dwordx4 v[166:169], v113, s[100:101]
	global_load_dwordx4 v[170:173], v206, s[100:101]
	global_load_dwordx4 v[174:177], v207, s[100:101]
	global_load_dwordx4 v[178:181], v208, s[100:101]
	global_load_dwordx4 v[182:185], v209, s[100:101]
	global_load_dwordx4 v[186:189], v210, s[100:101]
	global_load_dwordx4 v[190:193], v211, s[100:101]
	v_lshl_add_u64 v[212:213], s[100:101], 0, v[72:73]
	v_lshl_add_u64 v[212:213], v[212:213], 0, v[68:69]
	s_mov_b64 s[10:11], 0x4000
	v_lshl_add_u64 v[212:213], v[212:213], 0, s[10:11]
	global_load_dwordx2 v[214:215], v[212:213], off
	global_load_dwordx2 v[216:217], v[212:213], off offset:32
	global_load_dwordx2 v[218:219], v[212:213], off offset:64
	global_load_dwordx2 v[220:221], v[212:213], off offset:96
	ds_read_b128 v[138:141], v115 offset:44032
	ds_read_b128 v[142:145], v115 offset:44096
	ds_read_b128 v[146:149], v115 offset:46336
	ds_read_b128 v[150:153], v115 offset:46400
	ds_read_b128 v[154:157], v115 offset:48640
	ds_read_b128 v[194:197], v115 offset:48704
	ds_read_b128 v[198:201], v115 offset:50944
	ds_read_b128 v[202:205], v115 offset:51008
	v_cvt_pk_bf16_f32 v57, v222, s0
	ds_write_b16 v117, v57 offset:12784
	v_cvt_pk_bf16_f32 v57, v223, s0
	ds_write_b16 v117, v57 offset:13056
	v_cvt_pk_bf16_f32 v57, v224, s0
	ds_write_b16 v117, v57 offset:13328
	v_cvt_pk_bf16_f32 v57, v225, s0
	ds_write_b16 v117, v57 offset:13600
	s_waitcnt lgkmcnt(11)
	v_mfma_f32_16x16x32_bf16 v[28:31], v[138:141], v[36:39], v[28:31]
	s_waitcnt lgkmcnt(10)
	v_mfma_f32_16x16x32_bf16 v[28:31], v[142:145], v[32:35], v[28:31]
	ds_read_b128 v[138:141], v115 offset:53248
	ds_read_b128 v[142:145], v115 offset:53312
	s_waitcnt lgkmcnt(11)
	v_mfma_f32_16x16x32_bf16 v[20:23], v[146:149], v[36:39], v[20:23]
	s_waitcnt lgkmcnt(10)
	v_mfma_f32_16x16x32_bf16 v[20:23], v[150:153], v[32:35], v[20:23]
	ds_read_b128 v[146:149], v115 offset:55552
	ds_read_b128 v[150:153], v115 offset:55616
	s_waitcnt lgkmcnt(11)
	v_mfma_f32_16x16x32_bf16 v[0:3], v[154:157], v[36:39], v[0:3]
	s_waitcnt lgkmcnt(10)
	v_mfma_f32_16x16x32_bf16 v[0:3], v[194:197], v[32:35], v[0:3]
	ds_read_b128 v[154:157], v115 offset:57856
	ds_read_b128 v[194:197], v115 offset:57920
	s_waitcnt lgkmcnt(11)
	v_mfma_f32_16x16x32_bf16 v[16:19], v[198:201], v[36:39], v[16:19]
	s_waitcnt lgkmcnt(10)
	v_mfma_f32_16x16x32_bf16 v[16:19], v[202:205], v[32:35], v[16:19]
	ds_read_b128 v[198:201], v115 offset:60160
	ds_read_b128 v[202:205], v115 offset:60224
	s_waitcnt lgkmcnt(7)
	v_mfma_f32_16x16x32_bf16 v[4:7], v[138:141], v[36:39], v[4:7]
	s_waitcnt lgkmcnt(6)
	v_mfma_f32_16x16x32_bf16 v[4:7], v[142:145], v[32:35], v[4:7]
	s_waitcnt lgkmcnt(5)
	v_mfma_f32_16x16x32_bf16 v[12:15], v[146:149], v[36:39], v[12:15]
	s_waitcnt lgkmcnt(4)
	v_mfma_f32_16x16x32_bf16 v[12:15], v[150:153], v[32:35], v[12:15]
	s_waitcnt lgkmcnt(3)
	v_mfma_f32_16x16x32_bf16 v[8:11], v[154:157], v[36:39], v[8:11]
	s_waitcnt lgkmcnt(2)
	v_mfma_f32_16x16x32_bf16 v[8:11], v[194:197], v[32:35], v[8:11]
	s_waitcnt lgkmcnt(1)
	v_mfma_f32_16x16x32_bf16 v[24:27], v[198:201], v[36:39], v[24:27]
	s_waitcnt lgkmcnt(0)
	s_waitcnt lgkmcnt(0)
	s_barrier
	v_mfma_f32_16x16x32_bf16 v[24:27], v[202:205], v[32:35], v[24:27]
	v_add_u32_e32 v36, v66, v68
	v_cvt_pk_bf16_f32 v32, v28, v29
	v_cvt_pk_bf16_f32 v33, v30, v31
	v_cvt_pk_bf16_f32 v34, v20, v21
	v_cvt_pk_bf16_f32 v35, v22, v23
	v_add_u32_e32 v36, 0xf000, v36
	ds_write2_b64 v36, v[32:33], v[34:35] offset0:128 offset1:132
	v_cvt_pk_bf16_f32 v32, v0, v1
	v_cvt_pk_bf16_f32 v33, v2, v3
	v_cvt_pk_bf16_f32 v34, v16, v17
	v_cvt_pk_bf16_f32 v35, v18, v19
	ds_write2_b64 v36, v[32:33], v[34:35] offset0:136 offset1:140
	v_cvt_pk_bf16_f32 v32, v4, v5
	v_cvt_pk_bf16_f32 v33, v6, v7
	v_cvt_pk_bf16_f32 v34, v12, v13
	v_cvt_pk_bf16_f32 v35, v14, v15
	ds_write2_b64 v36, v[32:33], v[34:35] offset0:144 offset1:148
	v_cvt_pk_bf16_f32 v32, v8, v9
	v_cvt_pk_bf16_f32 v33, v10, v11
	v_cvt_pk_bf16_f32 v34, v24, v25
	v_cvt_pk_bf16_f32 v35, v26, v27
	ds_write2_b64 v36, v[32:33], v[34:35] offset0:152 offset1:156
	s_and_saveexec_b64 s[30:31], s[40:41]
	s_cbranch_execz .LBB0_1097
	v_and_b32_e32 v32, 64, v164
	v_add_u32_e32 v32, 64, v32
	v_xor_b32_e32 v33, 1, v164
	v_cmp_lt_i32_e32 vcc, v33, v32
	ds_read_b128 v[52:55], v118
	ds_read_b128 v[60:63], v118 offset:16
	v_cndmask_b32_e32 v33, v164, v33, vcc
	v_lshlrev_b32_e32 v121, 2, v33
	v_xor_b32_e32 v33, 2, v164
	v_cmp_lt_i32_e32 vcc, v33, v32
	s_waitcnt lgkmcnt(0)
	v_lshlrev_b32_e32 v80, 16, v62
	v_and_b32_e32 v81, 0xffff0000, v62
	v_cndmask_b32_e32 v33, v164, v33, vcc
	v_lshlrev_b32_e32 v120, 2, v33
	v_xor_b32_e32 v33, 4, v164
	v_cmp_lt_i32_e32 vcc, v33, v32
	v_lshlrev_b32_e32 v78, 16, v63
	v_and_b32_e32 v79, 0xffff0000, v63
	v_cndmask_b32_e32 v32, v164, v33, vcc
	v_lshlrev_b32_e32 v119, 2, v32
	v_lshl_add_u32 v32, s0, 6, v112
	v_ashrrev_i32_e32 v33, 31, v32
	v_lshlrev_b64 v[76:77], 12, v[32:33]
	v_lshl_or_b32 v76, v70, 1, v76
	v_lshl_add_u64 v[32:33], s[46:47], 0, v[76:77]
	s_waitcnt vmcnt(12)
	v_mov_b32_e32 v56, v232
	v_mov_b32_e32 v57, v233
	v_mov_b32_e32 v58, v234
	v_mov_b32_e32 v59, v235
	v_mov_b32_e32 v32, v236
	v_mov_b32_e32 v33, v237
	v_mov_b32_e32 v34, v238
	v_mov_b32_e32 v35, v239
	v_mov_b32_e32 v36, v240
	v_mov_b32_e32 v37, v241
	v_mov_b32_e32 v38, v242
	v_mov_b32_e32 v39, v243
	v_pk_mul_f32 v[62:63], v[80:81], v[80:81]
	v_pk_mul_f32 v[82:83], v[78:79], v[78:79]
	v_lshlrev_b32_e32 v130, 16, v56
	v_lshlrev_b32_e32 v84, 16, v34
	v_and_b32_e32 v85, 0xffff0000, v34
	v_mul_f32_e32 v34, 0xbfb8aa3b, v84
	v_exp_f32_e32 v86, v34
	v_mul_f32_e32 v34, 0xbfb8aa3b, v85
	v_exp_f32_e32 v87, v34
	v_and_b32_e32 v131, 0xffff0000, v56
	v_pk_add_f32 v[86:87], v[86:87], 1.0 op_sel_hi:[1,0]
	s_nop 0
	s_nop 0
	v_rcp_f32_e32 v87, v87
	s_nop 0
	s_nop 0
	v_lshlrev_b32_e32 v88, 16, v33
	v_and_b32_e32 v89, 0xffff0000, v33
	v_mul_f32_e32 v33, 0xbfb8aa3b, v88
	v_exp_f32_e32 v90, v33
	v_mul_f32_e32 v33, 0xbfb8aa3b, v89
	v_exp_f32_e32 v91, v33
	v_rcp_f32_e32 v86, v86
	s_nop 0
	v_pk_mul_f32 v[84:85], v[86:87], v[84:85]
	v_lshlrev_b32_e32 v86, 16, v61
	v_pk_add_f32 v[90:91], v[90:91], 1.0 op_sel_hi:[1,0]
	v_and_b32_e32 v87, 0xffff0000, v61
	v_pk_mul_f32 v[92:93], v[86:87], v[86:87]
	v_rcp_f32_e32 v91, v91
	s_nop 0
	s_nop 0
	v_lshlrev_b32_e32 v94, 16, v32
	v_and_b32_e32 v95, 0xffff0000, v32
	v_rcp_f32_e32 v90, v90
	s_nop 0
	v_mul_f32_e32 v32, 0xbfb8aa3b, v94
	v_mul_f32_e32 v33, 0xbfb8aa3b, v95
	v_exp_f32_e32 v32, v32
	v_exp_f32_e32 v33, v33
	v_pk_mul_f32 v[88:89], v[90:91], v[88:89]
	v_lshlrev_b32_e32 v90, 16, v60
	v_and_b32_e32 v91, 0xffff0000, v60
	v_pk_add_f32 v[32:33], v[32:33], 1.0 op_sel_hi:[1,0]
	v_pk_mul_f32 v[60:61], v[90:91], v[90:91]
	s_nop 0
	v_rcp_f32_e32 v33, v33
	s_nop 0
	s_nop 0
	v_lshlrev_b32_e32 v98, 16, v59
	v_rcp_f32_e32 v32, v32
	s_nop 0
	v_and_b32_e32 v99, 0xffff0000, v59
	v_mul_f32_e32 v34, 0xbfb8aa3b, v98
	v_exp_f32_e32 v100, v34
	v_mul_f32_e32 v34, 0xbfb8aa3b, v99
	v_exp_f32_e32 v101, v34
	v_pk_mul_f32 v[32:33], v[32:33], v[94:95]
	v_lshlrev_b32_e32 v94, 16, v55
	v_and_b32_e32 v95, 0xffff0000, v55
	v_pk_add_f32 v[100:101], v[100:101], 1.0 op_sel_hi:[1,0]
	v_pk_mul_f32 v[96:97], v[94:95], v[94:95]
	s_nop 0
	v_rcp_f32_e32 v101, v101
	s_nop 0
	s_nop 0
	v_lshlrev_b32_e32 v102, 16, v58
	v_rcp_f32_e32 v100, v100
	s_nop 0
	v_and_b32_e32 v103, 0xffff0000, v58
	v_mul_f32_e32 v34, 0xbfb8aa3b, v102
	v_exp_f32_e32 v58, v34
	v_mul_f32_e32 v34, 0xbfb8aa3b, v103
	v_exp_f32_e32 v59, v34
	v_pk_mul_f32 v[98:99], v[100:101], v[98:99]
	v_lshlrev_b32_e32 v100, 16, v54
	v_and_b32_e32 v101, 0xffff0000, v54
	v_pk_add_f32 v[58:59], v[58:59], 1.0 op_sel_hi:[1,0]
	v_pk_mul_f32 v[54:55], v[100:101], v[100:101]
	s_nop 0
	v_rcp_f32_e32 v59, v59
	s_nop 0
	s_nop 0
	v_lshlrev_b32_e32 v106, 16, v57
	v_rcp_f32_e32 v58, v58
	s_nop 0
	v_and_b32_e32 v107, 0xffff0000, v57
	v_mul_f32_e32 v34, 0xbfb8aa3b, v106
	v_exp_f32_e32 v122, v34
	v_mul_f32_e32 v34, 0xbfb8aa3b, v107
	v_exp_f32_e32 v123, v34
	v_pk_mul_f32 v[58:59], v[58:59], v[102:103]
	v_lshlrev_b32_e32 v102, 16, v53
	v_and_b32_e32 v103, 0xffff0000, v53
	v_pk_add_f32 v[122:123], v[122:123], 1.0 op_sel_hi:[1,0]
	v_pk_mul_f32 v[104:105], v[102:103], v[102:103]
	s_nop 0
	v_rcp_f32_e32 v123, v123
	s_nop 0
	s_nop 0
	v_rcp_f32_e32 v122, v122
	s_nop 0
	v_mul_f32_e32 v34, 0xbfb8aa3b, v130
	v_exp_f32_e32 v56, v34
	v_mul_f32_e32 v34, 0xbfb8aa3b, v131
	v_exp_f32_e32 v57, v34
	v_pk_mul_f32 v[106:107], v[122:123], v[106:107]
	v_lshlrev_b32_e32 v122, 16, v52
	v_and_b32_e32 v123, 0xffff0000, v52
	v_pk_add_f32 v[56:57], v[56:57], 1.0 op_sel_hi:[1,0]
	v_pk_mul_f32 v[52:53], v[122:123], v[122:123]
	s_nop 0
	v_rcp_f32_e32 v57, v57
	s_nop 0
	s_nop 0
	v_rcp_f32_e32 v56, v56
	s_nop 0
	v_add_f32_e32 v34, v52, v53
	v_add_f32_e32 v34, v104, v34
	v_add_f32_e32 v34, v105, v34
	v_add_f32_e32 v34, v54, v34
	v_add_f32_e32 v34, v55, v34
	v_add_f32_e32 v34, v96, v34
	v_add_f32_e32 v34, v97, v34
	v_add_f32_e32 v34, v60, v34
	v_add_f32_e32 v34, v61, v34
	v_add_f32_e32 v34, v92, v34
	v_add_f32_e32 v34, v93, v34
	v_add_f32_e32 v34, v62, v34
	v_add_f32_e32 v34, v63, v34
	v_add_f32_e32 v34, v82, v34
	v_add_f32_e32 v34, v83, v34
	ds_bpermute_b32 v52, v121, v34
	v_pk_mul_f32 v[56:57], v[56:57], v[130:131]
	s_waitcnt lgkmcnt(0)
	v_add_f32_e32 v34, v34, v52
	ds_bpermute_b32 v52, v120, v34
	s_waitcnt lgkmcnt(0)
	v_add_f32_e32 v34, v34, v52
	ds_bpermute_b32 v52, v119, v34
	s_waitcnt lgkmcnt(0)
	v_add_f32_e32 v34, v34, v52
	v_fmamk_f32 v34, v34, 0x3c000000, v162
	v_cmp_gt_f32_e32 vcc, s6, v34
	v_mul_f32_e32 v52, 0x4b800000, v34
	s_nop 0
	v_cndmask_b32_e32 v34, v34, v52, vcc
	v_rsq_f32_e32 v34, v34
	s_nop 0
	v_mul_f32_e32 v52, 0x45800000, v34
	v_cndmask_b32_e32 v52, v34, v52, vcc
	v_pk_mul_f32 v[54:55], v[52:53], v[122:123] op_sel_hi:[0,1]
	v_pk_mul_f32 v[48:49], v[48:49], v[54:55]
	v_pk_mul_f32 v[54:55], v[52:53], v[102:103] op_sel_hi:[0,1]
	v_pk_mul_f32 v[50:51], v[50:51], v[54:55]
	v_pk_mul_f32 v[48:49], v[56:57], v[48:49]
	v_pk_mul_f32 v[50:51], v[106:107], v[50:51]
	v_cvt_pk_bf16_f32 v48, v48, v49
	v_cvt_pk_bf16_f32 v49, v50, v51
	v_pk_mul_f32 v[50:51], v[52:53], v[100:101] op_sel_hi:[0,1]
	v_pk_mul_f32 v[44:45], v[44:45], v[50:51]
	s_nop 0
	v_pk_mul_f32 v[44:45], v[58:59], v[44:45]
	s_nop 0
	v_cvt_pk_bf16_f32 v50, v44, v45
	v_pk_mul_f32 v[44:45], v[52:53], v[94:95] op_sel_hi:[0,1]
	v_pk_mul_f32 v[44:45], v[46:47], v[44:45]
	s_nop 0
	v_pk_mul_f32 v[44:45], v[98:99], v[44:45]
	s_nop 0
	v_cvt_pk_bf16_f32 v51, v44, v45
	v_pk_mul_f32 v[44:45], v[52:53], v[90:91] op_sel_hi:[0,1]
	v_pk_mul_f32 v[40:41], v[40:41], v[44:45]
	s_nop 0
	v_pk_mul_f32 v[32:33], v[32:33], v[40:41]
	v_pk_mul_f32 v[40:41], v[52:53], v[86:87] op_sel_hi:[0,1]
	v_pk_mul_f32 v[40:41], v[42:43], v[40:41]
	v_cvt_pk_bf16_f32 v32, v32, v33
	v_pk_mul_f32 v[40:41], v[88:89], v[40:41]
	v_pk_mul_f32 v[42:43], v[52:53], v[78:79] op_sel_hi:[0,1]
	v_cvt_pk_bf16_f32 v33, v40, v41
	v_pk_mul_f32 v[40:41], v[52:53], v[80:81] op_sel_hi:[0,1]
	v_pk_mul_f32 v[36:37], v[36:37], v[40:41]
	v_pk_mul_f32 v[38:39], v[38:39], v[42:43]
	v_pk_mul_f32 v[36:37], v[84:85], v[36:37]
	s_nop 0
	v_cvt_pk_bf16_f32 v34, v36, v37
	v_lshlrev_b32_e32 v36, 16, v35
	v_and_b32_e32 v37, 0xffff0000, v35
	v_mul_f32_e32 v35, 0xbfb8aa3b, v36
	v_exp_f32_e32 v40, v35
	v_mul_f32_e32 v35, 0xbfb8aa3b, v37
	v_exp_f32_e32 v41, v35
	s_nop 0
	v_pk_add_f32 v[40:41], v[40:41], 1.0 op_sel_hi:[1,0]
	s_nop 0
	s_nop 0
	v_rcp_f32_e32 v41, v41
	s_nop 0
	s_nop 0
	v_rcp_f32_e32 v40, v40
	s_nop 0
	v_pk_mul_f32 v[36:37], v[40:41], v[36:37]
	s_nop 0
	v_pk_mul_f32 v[36:37], v[36:37], v[38:39]
	s_nop 0
	v_cvt_pk_bf16_f32 v35, v36, v37
	v_lshl_add_u64 v[36:37], s[48:49], 0, v[76:77]
	global_store_dwordx4 v[36:37], v[48:51], off
	global_store_dwordx4 v[36:37], v[32:35], off offset:16
	s_add_i32 s98, s0, 1
	v_lshl_add_u32 v206, s98, 6, v112
	v_ashrrev_i32_e32 v207, 31, v206
	v_lshlrev_b64 v[206:207], 12, v[206:207]
	v_lshl_or_b32 v206, v70, 1, v206
	v_lshl_add_u64 v[206:207], s[46:47], 0, v[206:207]
	global_load_dwordx4 v[232:235], v[206:207], off
	global_load_dwordx4 v[236:239], v[206:207], off offset:16
	s_branch .LBB0_1097
